# one-barrier ping-pong attention without the s_setprio switches (default priority everywhere)
# baseline (speedup 1.0000x reference)
.Lpp_a0_done:
	ds_read_b64_tr_b16 v[104:105], v166 offset:32768
	ds_read_b64_tr_b16 v[106:107], v158 offset:32768
	ds_read_b64_tr_b16 v[108:109], v167 offset:32768
	ds_read_b64_tr_b16 v[110:111], v160 offset:32768
	ds_read_b64_tr_b16 v[88:89], v168 offset:32768
	ds_read_b64_tr_b16 v[90:91], v162 offset:32768
	ds_read_b64_tr_b16 v[92:93], v169 offset:32768
	ds_read_b64_tr_b16 v[94:95], v163 offset:32768
	s_andn2_b64 vcc, exec, s[70:71]
	s_cbranch_vccnz .LBB0_1185
	ds_read_b128 v[0:3], v154 offset:16384
	ds_read_b128 v[4:7], v154 offset:24576
	ds_read_b128 v[170:173], v155 offset:16384
	ds_read_b128 v[174:177], v155 offset:24576
	ds_read_b128 v[182:185], v156 offset:16384
	ds_read_b128 v[186:189], v156 offset:24576
	ds_read_b128 v[194:197], v157 offset:16384
	ds_read_b128 v[226:229], v157 offset:24576
	s_waitcnt lgkmcnt(6)
	v_mfma_f32_32x32x16_bf16 v[128:143], v[0:3], v[238:241], 0
	v_mfma_f32_32x32x16_bf16 v[112:127], v[4:7], v[238:241], 0
	s_waitcnt lgkmcnt(4)
	v_mfma_f32_32x32x16_bf16 v[128:143], v[170:173], v[242:245], v[128:143]
	v_mfma_f32_32x32x16_bf16 v[112:127], v[174:177], v[242:245], v[112:127]
	s_waitcnt lgkmcnt(2)
	v_mfma_f32_32x32x16_bf16 v[128:143], v[182:185], v[246:249], v[128:143]
	v_mfma_f32_32x32x16_bf16 v[112:127], v[186:189], v[246:249], v[112:127]
	s_waitcnt lgkmcnt(0)
	v_mfma_f32_32x32x16_bf16 v[128:143], v[194:197], v[234:237], v[128:143]
	v_mfma_f32_32x32x16_bf16 v[112:127], v[226:229], v[234:237], v[112:127]

.Lpp_y0:
	s_waitcnt lgkmcnt(6)
	v_mfma_f32_32x32x16_bf16 v[48:63], v[178:181], v[84:87], v[48:63]
	s_and_b64 vcc, exec, s[42:43]
	s_waitcnt lgkmcnt(4)
	v_mfma_f32_32x32x16_bf16 v[64:79], v[182:185], v[84:87], v[64:79]
	s_waitcnt lgkmcnt(2)
	v_mfma_f32_32x32x16_bf16 v[32:47], v[186:189], v[84:87], v[32:47]
	s_waitcnt lgkmcnt(0)
	v_mfma_f32_32x32x16_bf16 v[16:31], v[190:193], v[84:87], v[16:31]
	s_cbranch_vccnz .LBB0_1197
	s_andn2_b64 s[42:43], exec, s[68:69]
	s_cmp_eq_u32 s19, 0
	s_cbranch_scc1 .LBB0_1188
	s_add_i32 s3, s74, 3
	s_cmp_ge_u32 s3, s17
	s_cbranch_scc1 .Lpp_b1_v
	s_mov_b32 m0, s27
	s_nop 0
	global_load_lds_dwordx4 v150, s[62:63]
	s_add_i32 m0, s27, 0x400
	s_nop 0
	global_load_lds_dwordx4 v144, s[62:63]

.Lpp_a1_done:
	ds_read_b64_tr_b16 v[136:137], v166 offset:49152
	ds_read_b64_tr_b16 v[138:139], v158 offset:49152
	ds_read_b64_tr_b16 v[140:141], v167 offset:49152
	ds_read_b64_tr_b16 v[142:143], v160 offset:49152
	ds_read_b64_tr_b16 v[120:121], v168 offset:49152
	ds_read_b64_tr_b16 v[122:123], v162 offset:49152
	ds_read_b64_tr_b16 v[124:125], v169 offset:49152
	ds_read_b64_tr_b16 v[126:127], v163 offset:49152
	s_and_b64 vcc, exec, s[42:43]
	s_cbranch_vccnz .LBB0_1196
	ds_read_b128 v[0:3], v154
	ds_read_b128 v[4:7], v154 offset:8192
	ds_read_b128 v[174:177], v155
	ds_read_b128 v[178:181], v155 offset:8192
	ds_read_b128 v[186:189], v156
	ds_read_b128 v[190:193], v156 offset:8192
	ds_read_b128 v[226:229], v157
	ds_read_b128 v[230:233], v157 offset:8192
	s_waitcnt lgkmcnt(6)
	v_mfma_f32_32x32x16_bf16 v[96:111], v[0:3], v[238:241], 0
	v_mfma_f32_32x32x16_bf16 v[80:95], v[4:7], v[238:241], 0
	s_waitcnt lgkmcnt(4)
	v_mfma_f32_32x32x16_bf16 v[96:111], v[174:177], v[242:245], v[96:111]
	v_mfma_f32_32x32x16_bf16 v[80:95], v[178:181], v[242:245], v[80:95]
	s_waitcnt lgkmcnt(2)
	v_mfma_f32_32x32x16_bf16 v[96:111], v[186:189], v[246:249], v[96:111]
	v_mfma_f32_32x32x16_bf16 v[80:95], v[190:193], v[246:249], v[80:95]
	s_waitcnt lgkmcnt(0)
	v_mfma_f32_32x32x16_bf16 v[96:111], v[226:229], v[234:237], v[96:111]
	v_mfma_f32_32x32x16_bf16 v[80:95], v[230:233], v[234:237], v[80:95]

.Lpp_y1:
	s_waitcnt lgkmcnt(6)
	v_mfma_f32_32x32x16_bf16 v[48:63], v[178:181], v[116:119], v[48:63]
	s_waitcnt lgkmcnt(4)
	v_mfma_f32_32x32x16_bf16 v[64:79], v[182:185], v[116:119], v[64:79]
	s_waitcnt lgkmcnt(2)
	v_mfma_f32_32x32x16_bf16 v[32:47], v[186:189], v[116:119], v[32:47]
	s_waitcnt lgkmcnt(0)
	v_mfma_f32_32x32x16_bf16 v[16:31], v[170:173], v[116:119], v[16:31]
